# static s_setprio 1 for the later-dispatched half of the grid in every phase except attention (which keeps its own per-section scheme)
# baseline (speedup 1.0000x reference)
.LBB0_7:
	s_mov_b32 s38, s42
	s_mov_b32 s0, 0x1bff
	s_bitcmp1_b32 s0, s42
	s_cbranch_scc0 .Lgemm_np
	s_bitcmp1_b32 s50, 8
	s_cbranch_scc0 .Lgemm_np
	s_setprio 1
